# v17 + grid barrier: XCD leader posts its generation word right after the chip-wide release word (no wait on the TOPGEN atomic)
# speedup vs baseline: 1.0057x; 1.0057x over previous
; __device__ __forceinline__ void xcd_barrier(const XcdBarrier& b) {
;     ...
;             asm volatile("s_waitcnt vmcnt(0)" ::: "memory");
;             (void)__hip_atomic_fetch_add(&bar[XB_XGEN(b.x)], 1u, __ATOMIC_RELAXED, __HIP_MEMORY_SCOPE_AGENT);
.LBB0_110:
	s_or_b64 exec, exec, s[10:11]
	s_mov_b64 s[10:11], exec
	s_nop 0
	v_mbcnt_lo_u32_b32 v1, s10, 0
	v_mbcnt_hi_u32_b32 v1, s11, v1
	v_cmp_eq_u32_e64 s[0:1], 0, v1
	s_and_saveexec_b64 s[12:13], s[0:1]
	s_cbranch_execz .LBB0_112
	s_bcnt1_i32_b64 s0, s[10:11]
	v_mov_b32_e32 v1, 0x2000
	v_mov_b32_e32 v3, s0
	global_atomic_add v1, v3, s[8:9] offset:1024

; __device__ __forceinline__ void xcd_barrier(const XcdBarrier& b) {
;     ...
;             asm volatile("s_waitcnt vmcnt(0)" ::: "memory");
;             (void)__hip_atomic_fetch_add(&bar[XB_XGEN(b.x)], 1u, __ATOMIC_RELAXED, __HIP_MEMORY_SCOPE_AGENT);
.LBB0_257:
	s_or_b64 exec, exec, s[10:11]
	s_mov_b64 s[10:11], exec
	s_nop 0
	v_mbcnt_lo_u32_b32 v2, s10, 0
	v_mbcnt_hi_u32_b32 v2, s11, v2
	v_cmp_eq_u32_e64 s[0:1], 0, v2
	s_and_saveexec_b64 s[12:13], s[0:1]
	s_cbranch_execz .LBB0_259
	s_bcnt1_i32_b64 s0, s[10:11]
	v_mov_b32_e32 v2, 0x2000
	v_mov_b32_e32 v4, s0
	global_atomic_add v2, v4, s[8:9] offset:1024

; __device__ __forceinline__ void xcd_barrier(const XcdBarrier& b) {
;     ...
;             asm volatile("s_waitcnt vmcnt(0)" ::: "memory");
;             (void)__hip_atomic_fetch_add(&bar[XB_XGEN(b.x)], 1u, __ATOMIC_RELAXED, __HIP_MEMORY_SCOPE_AGENT);
.LBB0_740:
	s_or_b64 exec, exec, s[12:13]
	s_mov_b64 s[12:13], exec
	s_nop 0
	v_mbcnt_lo_u32_b32 v2, s12, 0
	v_mbcnt_hi_u32_b32 v2, s13, v2
	v_cmp_eq_u32_e64 s[0:1], 0, v2
	s_and_saveexec_b64 s[14:15], s[0:1]
	s_cbranch_execz .LBB0_742
	s_bcnt1_i32_b64 s0, s[12:13]
	v_mov_b32_e32 v2, 0x2000
	v_mov_b32_e32 v4, s0
	global_atomic_add v2, v4, s[10:11] offset:1024
